# gate log-sigmoid: single pass on |x| plus min(x,0) instead of two sign branches run back to back
# speedup vs baseline: 1.0129x; 1.0007x over previous
; #define LAS __attribute__((address_space(3)))
; __device__ __forceinline__ unsigned pk2(float lo, float hi) { return f2bf(lo) | (f2bf(hi) << 16); }
; template <int SRC, int EXTRA, bool OUT8 = false> ...
;     ...
;         if (stats && lane == 0) { stats[2 * row] = mean; stats[2 * row + 1] = rstd; }
; #pragma unroll
;         for (int j = 0; j < 4; ++j) { v[j] = v[j] * rstd * gv[j] + bv[j]; if (of32) *(f32x4*)(of32 + (size_t)row * 1024 + 256 * j + 4 * lane) = v[j];
;             if (obf) { if constexpr (OUT8) { int w = 0; w = __builtin_amdgcn_cvt_pk_fp8_f32(v[j].x, v[j].y, w, false); w = __builtin_amdgcn_cvt_pk_fp8_f32(v[j].z, v[j].w, w, true); *(unsigned*)((unsigned char*)obf + (size_t)row * 1024 + 256 * j + 4 * lane) = (unsigned)w; }
;                 else { v2u o; o.x = pk2(v[j].x, v[j].y); o.y = pk2(v[j].z, v[j].w); *(v2u*)(obf + (size_t)row * 1024 + 256 * j + 4 * lane) = o; } } }
;         if (EXTRA != 0) {
;             float d[8];
; #pragma unroll
;             for (int e = 0; e < 8; ++e) { float a = 0.f;
; #pragma unroll
;                 for (int j = 0; j < 4; ++j) { const f32x4 w = *(const LAS f32x4*)(w8s + e * 1024 + 256 * j + 4 * lane); a += (v[j].x * w.x + v[j].y * w.y) + (v[j].z * w.z + v[j].w * w.w); }
;                 d[e] = wave_sum(a); }
.LBB0_61:
	s_or_b64 exec, exec, s[22:23]
	v_pk_mul_f32 v[40:41], v[46:47], v[52:53] op_sel_hi:[1,0]
	v_pk_mul_f32 v[36:37], v[66:67], v[52:53] op_sel_hi:[1,0]
	v_pk_fma_f32 v[40:41], v[2:3], v[40:41], v[10:11]
	v_pk_fma_f32 v[36:37], v[4:5], v[36:37], v[12:13]
	v_bfe_u32 v46, v40, 16, 1
	v_add3_u32 v46, v40, v46, s35
	v_bfe_u32 v47, v41, 16, 1
	v_lshrrev_b32_e32 v46, 16, v46
	v_add3_u32 v47, v41, v47, s35
	v_and_or_b32 v46, v47, s46, v46
	v_bfe_u32 v47, v36, 16, 1
	v_add3_u32 v47, v36, v47, s35
	v_bfe_u32 v63, v37, 16, 1
	v_lshrrev_b32_e32 v47, 16, v47
	v_add3_u32 v63, v37, v63, s35
	v_and_or_b32 v47, v63, s46, v47
	global_store_dwordx2 v[58:59], v[46:47], off
	v_pk_mul_f32 v[44:45], v[44:45], v[52:53] op_sel_hi:[1,0]
	v_pk_mul_f32 v[46:47], v[42:43], v[52:53] op_sel_hi:[1,0]
	v_pk_fma_f32 v[42:43], v[8:9], v[44:45], v[16:17]
	v_pk_fma_f32 v[44:45], v[6:7], v[46:47], v[14:15]
	v_bfe_u32 v63, v43, 16, 1
	v_bfe_u32 v46, v44, 16, 1
	v_add3_u32 v46, v44, v46, s35
	v_bfe_u32 v47, v45, 16, 1
	v_lshrrev_b32_e32 v46, 16, v46
	v_add3_u32 v47, v45, v47, s35
	v_and_or_b32 v46, v47, s46, v46
	v_bfe_u32 v47, v42, 16, 1
	v_add3_u32 v47, v42, v47, s35
	v_lshrrev_b32_e32 v47, 16, v47
	v_add3_u32 v63, v43, v63, s35
	v_and_or_b32 v47, v63, s46, v47
	global_store_dwordx2 v[58:59], v[46:47], off offset:512
	v_pk_mul_f32 v[46:47], v[64:65], v[52:53] op_sel_hi:[1,0]
	v_pk_mul_f32 v[64:65], v[38:39], v[52:53] op_sel_hi:[1,0]
	v_pk_fma_f32 v[38:39], v[20:21], v[46:47], v[28:29]
	v_pk_fma_f32 v[46:47], v[18:19], v[64:65], v[26:27]
	v_bfe_u32 v65, v39, 16, 1
	v_bfe_u32 v63, v46, 16, 1
	v_add3_u32 v63, v46, v63, s35
	v_bfe_u32 v64, v47, 16, 1
	v_lshrrev_b32_e32 v63, 16, v63
	v_add3_u32 v64, v47, v64, s35
	v_and_or_b32 v64, v64, s46, v63
	v_bfe_u32 v63, v38, 16, 1
	v_add3_u32 v63, v38, v63, s35
	v_lshrrev_b32_e32 v63, 16, v63
	v_add3_u32 v65, v39, v65, s35
	v_and_or_b32 v65, v65, s46, v63
	global_store_dwordx2 v[58:59], v[64:65], off offset:1024
	v_pk_mul_f32 v[48:49], v[48:49], v[52:53] op_sel_hi:[1,0]
	v_pk_mul_f32 v[64:65], v[34:35], v[52:53] op_sel_hi:[1,0]
	v_pk_fma_f32 v[34:35], v[24:25], v[48:49], v[32:33]
	v_pk_fma_f32 v[48:49], v[22:23], v[64:65], v[30:31]
	v_bfe_u32 v73, v35, 16, 1
	v_bfe_u32 v52, v48, 16, 1
	v_add3_u32 v52, v48, v52, s35
	v_bfe_u32 v63, v49, 16, 1
	v_lshrrev_b32_e32 v52, 16, v52
	v_add3_u32 v63, v49, v63, s35
	v_and_or_b32 v74, v63, s46, v52
	v_bfe_u32 v52, v34, 16, 1
	v_add3_u32 v52, v34, v52, s35
	v_lshrrev_b32_e32 v63, 16, v52
	v_add_u32_e32 v52, 0, v50
	v_add3_u32 v73, v35, v73, s35
	v_and_or_b32 v75, v73, s46, v63
	global_store_dwordx2 v[58:59], v[74:75], off offset:1536
	s_waitcnt lgkmcnt(0)
	v_pk_mul_f32 v[104:105], v[40:41], v[124:125]
	v_pk_mul_f32 v[106:107], v[40:41], v[140:141]
	v_pk_mul_f32 v[108:109], v[40:41], v[156:157]
	v_pk_mul_f32 v[110:111], v[40:41], v[172:173]
	v_pk_fma_f32 v[104:105], v[36:37], v[126:127], v[104:105]
	v_pk_fma_f32 v[106:107], v[36:37], v[142:143], v[106:107]
	v_pk_fma_f32 v[108:109], v[36:37], v[158:159], v[108:109]
	v_pk_fma_f32 v[110:111], v[36:37], v[174:175], v[110:111]
	ds_read_b128 v[124:127], v50 offset:16384
	ds_read_b128 v[140:143], v50 offset:20480
	ds_read_b128 v[156:159], v50 offset:24576
	ds_read_b128 v[172:175], v50 offset:28672
	v_pk_fma_f32 v[104:105], v[44:45], v[128:129], v[104:105]
	v_pk_fma_f32 v[106:107], v[44:45], v[144:145], v[106:107]
	v_pk_fma_f32 v[108:109], v[44:45], v[160:161], v[108:109]
	v_pk_fma_f32 v[110:111], v[44:45], v[176:177], v[110:111]
	v_pk_fma_f32 v[104:105], v[42:43], v[130:131], v[104:105]
	v_pk_fma_f32 v[106:107], v[42:43], v[146:147], v[106:107]
	v_pk_fma_f32 v[108:109], v[42:43], v[162:163], v[108:109]
	v_pk_fma_f32 v[110:111], v[42:43], v[178:179], v[110:111]
	ds_read_b128 v[128:131], v50 offset:17408
	ds_read_b128 v[144:147], v50 offset:21504
	ds_read_b128 v[160:163], v50 offset:25600
	ds_read_b128 v[176:179], v50 offset:29696
	v_pk_fma_f32 v[104:105], v[46:47], v[132:133], v[104:105]
	v_pk_fma_f32 v[106:107], v[46:47], v[148:149], v[106:107]
	v_pk_fma_f32 v[108:109], v[46:47], v[164:165], v[108:109]
	v_pk_fma_f32 v[110:111], v[46:47], v[180:181], v[110:111]
	v_pk_fma_f32 v[104:105], v[38:39], v[134:135], v[104:105]
	v_pk_fma_f32 v[106:107], v[38:39], v[150:151], v[106:107]
	v_pk_fma_f32 v[108:109], v[38:39], v[166:167], v[108:109]
	v_pk_fma_f32 v[110:111], v[38:39], v[182:183], v[110:111]
	ds_read_b128 v[132:135], v50 offset:18432
	ds_read_b128 v[148:151], v50 offset:22528
	ds_read_b128 v[164:167], v50 offset:26624
	ds_read_b128 v[180:183], v50 offset:30720
	v_pk_fma_f32 v[104:105], v[48:49], v[136:137], v[104:105]
	v_pk_fma_f32 v[106:107], v[48:49], v[152:153], v[106:107]
	v_pk_fma_f32 v[108:109], v[48:49], v[168:169], v[108:109]
	v_pk_fma_f32 v[110:111], v[48:49], v[184:185], v[110:111]
	v_pk_fma_f32 v[104:105], v[34:35], v[138:139], v[104:105]
	v_pk_fma_f32 v[106:107], v[34:35], v[154:155], v[106:107]
	v_pk_fma_f32 v[108:109], v[34:35], v[170:171], v[108:109]
	v_pk_fma_f32 v[110:111], v[34:35], v[186:187], v[110:111]
	ds_read_b128 v[136:139], v50 offset:19456
	ds_read_b128 v[152:155], v50 offset:23552
	ds_read_b128 v[168:171], v50 offset:27648
	ds_read_b128 v[184:187], v50 offset:31744
	v_add_f32_e32 v96, v104, v105
	v_add_f32_e32 v97, v106, v107
	v_add_f32_e32 v98, v108, v109
	v_add_f32_e32 v99, v110, v111
	s_waitcnt lgkmcnt(12)
	v_pk_mul_f32 v[104:105], v[40:41], v[124:125]
	v_pk_mul_f32 v[106:107], v[40:41], v[140:141]
	v_pk_mul_f32 v[108:109], v[40:41], v[156:157]
	v_pk_mul_f32 v[110:111], v[40:41], v[172:173]
	v_pk_fma_f32 v[104:105], v[36:37], v[126:127], v[104:105]
	v_pk_fma_f32 v[106:107], v[36:37], v[142:143], v[106:107]
	v_pk_fma_f32 v[108:109], v[36:37], v[158:159], v[108:109]
	v_pk_fma_f32 v[110:111], v[36:37], v[174:175], v[110:111]
	s_waitcnt lgkmcnt(8)
; #define LAS __attribute__((address_space(3)))
; template <int SRC, int EXTRA, bool OUT8 = false> ...
;     ...
;             for (int e = 0; e < 8; ++e) { float a = 0.f;
; #pragma unroll
;                 for (int j = 0; j < 4; ++j) { const f32x4 w = *(const LAS f32x4*)(w8s + e * 1024 + 256 * j + 4 * lane); a += (v[j].x * w.x + v[j].y * w.y) + (v[j].z * w.z + v[j].w * w.w); }
;                 d[e] = wave_sum(a); }
;             if (EXTRA == 1) {
;                 float x = d[0];
; #pragma unroll
;                 for (int e = 1; e < 8; ++e) x = (lane == e) ? d[e] : x;
	v_pk_fma_f32 v[104:105], v[44:45], v[128:129], v[104:105]
	v_pk_fma_f32 v[106:107], v[44:45], v[144:145], v[106:107]
	v_pk_fma_f32 v[108:109], v[44:45], v[160:161], v[108:109]
	v_pk_fma_f32 v[110:111], v[44:45], v[176:177], v[110:111]
	v_pk_fma_f32 v[104:105], v[42:43], v[130:131], v[104:105]
	v_pk_fma_f32 v[106:107], v[42:43], v[146:147], v[106:107]
	v_pk_fma_f32 v[108:109], v[42:43], v[162:163], v[108:109]
	v_pk_fma_f32 v[110:111], v[42:43], v[178:179], v[110:111]
	s_waitcnt lgkmcnt(4)
	v_pk_fma_f32 v[104:105], v[46:47], v[132:133], v[104:105]
	v_pk_fma_f32 v[106:107], v[46:47], v[148:149], v[106:107]
	v_pk_fma_f32 v[108:109], v[46:47], v[164:165], v[108:109]
	v_pk_fma_f32 v[110:111], v[46:47], v[180:181], v[110:111]
	v_pk_fma_f32 v[104:105], v[38:39], v[134:135], v[104:105]
	v_pk_fma_f32 v[106:107], v[38:39], v[150:151], v[106:107]
	v_pk_fma_f32 v[108:109], v[38:39], v[166:167], v[108:109]
	v_pk_fma_f32 v[110:111], v[38:39], v[182:183], v[110:111]
	s_waitcnt lgkmcnt(0)
	v_pk_fma_f32 v[104:105], v[48:49], v[136:137], v[104:105]
	v_pk_fma_f32 v[106:107], v[48:49], v[152:153], v[106:107]
	v_pk_fma_f32 v[108:109], v[48:49], v[168:169], v[108:109]
	v_pk_fma_f32 v[110:111], v[48:49], v[184:185], v[110:111]
	v_pk_fma_f32 v[104:105], v[34:35], v[138:139], v[104:105]
	v_pk_fma_f32 v[106:107], v[34:35], v[154:155], v[106:107]
	v_pk_fma_f32 v[108:109], v[34:35], v[170:171], v[108:109]
	v_pk_fma_f32 v[110:111], v[34:35], v[186:187], v[110:111]
	v_add_f32_e32 v100, v104, v105
	v_add_f32_e32 v101, v106, v107
	v_add_f32_e32 v102, v108, v109
	v_add_f32_e32 v103, v110, v111
	s_nop 0
	v_add_f32_dpp v104, v96, v96 quad_perm:[1,0,3,2] row_mask:0xf bank_mask:0xf
	v_add_f32_dpp v105, v97, v97 quad_perm:[1,0,3,2] row_mask:0xf bank_mask:0xf
	v_cndmask_b32_e64 v112, v104, v105, s[58:59]
	v_add_f32_dpp v106, v98, v98 quad_perm:[1,0,3,2] row_mask:0xf bank_mask:0xf
	v_add_f32_dpp v107, v99, v99 quad_perm:[1,0,3,2] row_mask:0xf bank_mask:0xf
	v_cndmask_b32_e64 v113, v106, v107, s[58:59]
	v_add_f32_dpp v108, v100, v100 quad_perm:[1,0,3,2] row_mask:0xf bank_mask:0xf
	v_add_f32_dpp v109, v101, v101 quad_perm:[1,0,3,2] row_mask:0xf bank_mask:0xf
	v_cndmask_b32_e64 v114, v108, v109, s[58:59]
	v_add_f32_dpp v110, v102, v102 quad_perm:[1,0,3,2] row_mask:0xf bank_mask:0xf
	v_add_f32_dpp v111, v103, v103 quad_perm:[1,0,3,2] row_mask:0xf bank_mask:0xf
	v_cndmask_b32_e64 v115, v110, v111, s[58:59]
	v_add_f32_dpp v104, v112, v112 quad_perm:[2,3,0,1] row_mask:0xf bank_mask:0xf
	v_add_f32_dpp v105, v113, v113 quad_perm:[2,3,0,1] row_mask:0xf bank_mask:0xf
	v_cndmask_b32_e64 v116, v104, v105, s[60:61]
	v_add_f32_dpp v106, v114, v114 quad_perm:[2,3,0,1] row_mask:0xf bank_mask:0xf
	v_add_f32_dpp v107, v115, v115 quad_perm:[2,3,0,1] row_mask:0xf bank_mask:0xf
	v_cndmask_b32_e64 v117, v106, v107, s[60:61]
	v_add_f32_dpp v104, v116, v116 row_shl:4 row_mask:0xf bank_mask:0x5
	v_add_f32_dpp v104, v116, v116 row_shr:4 row_mask:0xf bank_mask:0xa
	v_add_f32_dpp v105, v117, v117 row_shl:4 row_mask:0xf bank_mask:0x5
	v_add_f32_dpp v105, v117, v117 row_shr:4 row_mask:0xf bank_mask:0xa
	v_cndmask_b32_e64 v118, v104, v105, s[62:63]
	s_nop 1
	v_add_f32_dpp v119, v118, v118 row_ror:8 row_mask:0xf bank_mask:0xf
	v_mov_b32_e32 v104, v119
	v_mov_b32_e32 v120, v119
	s_nop 1
	v_permlane16_swap_b32_e32 v104, v120
	v_cndmask_b32_e64 v104, v120, v104, s[98:99]
	v_add_f32_e32 v119, v119, v104
	v_mov_b32_e32 v104, v119
	v_mov_b32_e32 v120, v119
	s_nop 1
	v_permlane32_swap_b32_e32 v104, v120
	v_cndmask_b32_e64 v104, v120, v104, s[100:101]
	v_add_f32_e32 v34, v119, v104
	s_and_saveexec_b64 s[22:23], s[6:7]
	s_cbranch_execz .LBB0_58
; template <int SRC, int EXTRA, bool OUT8 = false> ...
;     ...
;                 if (lane < 8) { x += bf8[lane]; const float ls = (x >= 0.f) ? -log1pf(__expf(-x)) : (x - log1pf(__expf(x))); logf[(size_t)lane * M + row] = ls; }
	v_add_f32_e32 v34, v34, v206
	v_mov_b32_e32 v121, v34
	v_and_b32_e32 v34, 0x7fffffff, v34
	s_mov_b64 s[42:43], exec
	v_mul_f32_e32 v34, 0xbfb8aa3b, v34
	v_exp_f32_e32 v48, v34
	s_nop 0
	v_add_f32_e32 v36, 1.0, v48
	v_frexp_mant_f32_e32 v38, v36
	v_cvt_f64_f32_e32 v[34:35], v36
	v_frexp_exp_i32_f64_e32 v34, v[34:35]
	v_cmp_gt_f32_e32 vcc, s47, v38
	v_add_f32_e32 v37, -1.0, v36
	v_sub_f32_e32 v39, v37, v36
	v_subbrev_co_u32_e32 v42, vcc, 0, v34, vcc
	v_sub_u32_e32 v34, 0, v42
	v_sub_f32_e32 v37, v48, v37
	v_add_f32_e32 v39, 1.0, v39
	v_ldexp_f32 v35, v36, v34
	v_add_f32_e32 v37, v37, v39
	v_add_f32_e32 v36, -1.0, v35
	v_add_f32_e32 v38, 1.0, v35
	v_ldexp_f32 v34, v37, v34
	v_add_f32_e32 v37, 1.0, v36
	v_add_f32_e32 v39, -1.0, v38
	v_sub_f32_e32 v37, v35, v37
	v_sub_f32_e32 v35, v35, v39
	v_add_f32_e32 v37, v34, v37
	v_add_f32_e32 v34, v34, v35
	v_add_f32_e32 v43, v38, v34
	v_rcp_f32_e32 v45, v43
	v_sub_f32_e32 v35, v43, v38
	v_sub_f32_e32 v44, v34, v35
	v_add_f32_e32 v35, v36, v37
	v_mul_f32_e32 v47, v35, v45
	v_sub_f32_e32 v34, v35, v36
	v_mul_f32_e32 v36, v43, v47
	v_fma_f32 v38, v47, v43, -v36
	v_fmac_f32_e32 v38, v47, v44
	v_sub_f32_e32 v46, v37, v34
	v_add_f32_e32 v34, v36, v38
	v_sub_f32_e32 v37, v35, v34
	v_pk_add_f32 v[40:41], v[34:35], v[36:37] neg_lo:[0,1] neg_hi:[0,1]
	v_mov_b32_e32 v39, v34
	v_pk_add_f32 v[34:35], v[40:41], v[38:39] neg_lo:[0,1] neg_hi:[0,1]
	v_cmp_neq_f32_e32 vcc, s49, v48
	v_add_f32_e32 v35, v46, v35
	v_add_f32_e32 v34, v34, v35
	v_add_f32_e32 v35, v37, v34
	v_mul_f32_e32 v46, v45, v35
	v_mul_f32_e32 v36, v43, v46
	v_fma_f32 v38, v46, v43, -v36
	v_fmac_f32_e32 v38, v46, v44
	v_sub_f32_e32 v37, v37, v35
	v_add_f32_e32 v43, v34, v37
	v_add_f32_e32 v34, v36, v38
	v_sub_f32_e32 v37, v35, v34
	v_pk_add_f32 v[40:41], v[34:35], v[36:37] neg_lo:[0,1] neg_hi:[0,1]
	v_mov_b32_e32 v39, v34
	v_pk_add_f32 v[34:35], v[40:41], v[38:39] neg_lo:[0,1] neg_hi:[0,1]
	s_nop 0
	v_add_f32_e32 v35, v43, v35
	v_add_f32_e32 v34, v34, v35
	v_add_f32_e32 v35, v47, v46
	v_add_f32_e32 v34, v37, v34
	v_sub_f32_e32 v36, v35, v47
	v_mul_f32_e32 v34, v45, v34
	v_sub_f32_e32 v36, v46, v36
	v_add_f32_e32 v36, v36, v34
	v_add_f32_e32 v38, v35, v36
	v_mul_f32_e32 v39, v38, v38
	v_fmamk_f32 v34, v39, 0x3e9b6dac, v69
	v_fmaak_f32 v63, v39, v34, 0x3f2aaada
	v_cvt_f32_i32_e32 v34, v42
	v_sub_f32_e32 v35, v38, v35
	v_sub_f32_e32 v35, v36, v35
	v_ldexp_f32 v40, v35, 1
	v_mul_f32_e32 v35, v38, v39
	v_ldexp_f32 v37, v38, 1
	v_pk_mul_f32 v[38:39], v[34:35], v[62:63]
	s_nop 0
	v_fma_f32 v36, v34, s48, -v38
	v_fmac_f32_e32 v36, 0xb102e308, v34
	v_pk_add_f32 v[34:35], v[38:39], v[36:37]
	s_nop 0
	v_sub_f32_e32 v37, v35, v37
	v_sub_f32_e32 v37, v39, v37
	v_add_f32_e32 v41, v40, v37
	v_mov_b32_e32 v40, v38
	v_pk_add_f32 v[38:39], v[34:35], v[38:39] neg_lo:[0,1] neg_hi:[0,1]
	v_pk_add_f32 v[42:43], v[34:35], v[40:41]
	v_mov_b32_e32 v37, v34
	v_mov_b32_e32 v39, v43
	v_pk_add_f32 v[44:45], v[36:37], v[38:39] neg_lo:[0,1] neg_hi:[0,1]
	v_pk_add_f32 v[36:37], v[36:37], v[38:39]
	v_mov_b32_e32 v40, v41
	v_pk_add_f32 v[38:39], v[36:37], v[34:35] op_sel:[1,0] op_sel_hi:[0,1] neg_lo:[0,1] neg_hi:[0,1]
	v_pk_add_f32 v[46:47], v[42:43], v[38:39] op_sel_hi:[1,0] neg_lo:[0,1] neg_hi:[0,1]
	v_mov_b32_e32 v42, v43
	v_mov_b32_e32 v43, v37
	v_pk_mov_b32 v[38:39], v[34:35], v[38:39] op_sel:[1,0]
	v_mov_b32_e32 v41, v34
	v_pk_add_f32 v[38:39], v[42:43], v[38:39] neg_lo:[0,1] neg_hi:[0,1]
	v_mov_b32_e32 v46, v44
	v_pk_add_f32 v[34:35], v[40:41], v[38:39] neg_lo:[0,1] neg_hi:[0,1]
	v_mov_b32_e32 v45, v37
	v_pk_add_f32 v[38:39], v[46:47], v[34:35]
	s_nop 0
	v_pk_add_f32 v[40:41], v[38:39], v[38:39] op_sel:[0,1] op_sel_hi:[1,0]
	s_nop 0
	v_pk_add_f32 v[36:37], v[36:37], v[40:41] op_sel:[1,0] op_sel_hi:[0,1]
	v_mov_b32_e32 v39, v36
	v_pk_add_f32 v[42:43], v[38:39], v[44:45] neg_lo:[0,1] neg_hi:[0,1]
	v_mov_b32_e32 v35, v40
	v_sub_f32_e32 v37, v38, v42
	v_pk_add_f32 v[34:35], v[34:35], v[42:43] neg_lo:[0,1] neg_hi:[0,1]
	v_sub_f32_e32 v37, v44, v37
	v_add_f32_e32 v34, v34, v37
	v_add_f32_e32 v34, v34, v35
	v_add_f32_e32 v34, v36, v34
	v_cndmask_b32_e32 v34, v70, v34, vcc
	v_cmp_ngt_f32_e32 vcc, -1.0, v48
	s_nop 1
	v_cndmask_b32_e32 v34, v71, v34, vcc
	v_cmp_neq_f32_e32 vcc, -1.0, v48
	s_nop 1
	v_cndmask_b32_e32 v34, v72, v34, vcc
	v_cmp_lt_f32_e64 vcc, |v48|, s50
	s_nop 1
	v_cndmask_b32_e32 v34, v34, v48, vcc
	v_xor_b32_e32 v35, 0x80000000, v34
	v_min_f32_e32 v121, 0, v121
	v_add_f32_e32 v35, v121, v35
	s_branch .LBB0_57

; #define LAS __attribute__((address_space(3)))
; __device__ __forceinline__ unsigned pk2(float lo, float hi) { return f2bf(lo) | (f2bf(hi) << 16); }
; template <int SRC, int EXTRA, bool OUT8 = false> ...
;     ...
;         if (stats && lane == 0) { stats[2 * row] = mean; stats[2 * row + 1] = rstd; }
; #pragma unroll
;         for (int j = 0; j < 4; ++j) { v[j] = v[j] * rstd * gv[j] + bv[j]; if (of32) *(f32x4*)(of32 + (size_t)row * 1024 + 256 * j + 4 * lane) = v[j];
;             if (obf) { if constexpr (OUT8) { int w = 0; w = __builtin_amdgcn_cvt_pk_fp8_f32(v[j].x, v[j].y, w, false); w = __builtin_amdgcn_cvt_pk_fp8_f32(v[j].z, v[j].w, w, true); *(unsigned*)((unsigned char*)obf + (size_t)row * 1024 + 256 * j + 4 * lane) = (unsigned)w; }
;                 else { v2u o; o.x = pk2(v[j].x, v[j].y); o.y = pk2(v[j].z, v[j].w); *(v2u*)(obf + (size_t)row * 1024 + 256 * j + 4 * lane) = o; } } }
;         if (EXTRA != 0) {
;             float d[8];
; #pragma unroll
;             for (int e = 0; e < 8; ++e) { float a = 0.f;
; #pragma unroll
;                 for (int j = 0; j < 4; ++j) { const f32x4 w = *(const LAS f32x4*)(w8s + e * 1024 + 256 * j + 4 * lane); a += (v[j].x * w.x + v[j].y * w.y) + (v[j].z * w.z + v[j].w * w.w); }
;                 d[e] = wave_sum(a); }
.LBB0_1059:
	s_or_b64 exec, exec, s[28:29]
	v_pk_mul_f32 v[38:39], v[44:45], v[50:51] op_sel_hi:[1,0]
	v_pk_mul_f32 v[34:35], v[64:65], v[50:51] op_sel_hi:[1,0]
	v_pk_fma_f32 v[38:39], v[0:1], v[38:39], v[8:9]
	v_pk_fma_f32 v[34:35], v[2:3], v[34:35], v[10:11]
	v_bfe_u32 v44, v38, 16, 1
	v_add3_u32 v44, v38, v44, s35
	v_bfe_u32 v45, v39, 16, 1
	v_lshrrev_b32_e32 v44, 16, v44
	v_add3_u32 v45, v39, v45, s35
	v_and_or_b32 v44, v45, s42, v44
	v_bfe_u32 v45, v34, 16, 1
	v_add3_u32 v45, v34, v45, s35
	v_bfe_u32 v61, v35, 16, 1
	v_lshrrev_b32_e32 v45, 16, v45
	v_add3_u32 v61, v35, v61, s35
	v_and_or_b32 v45, v61, s42, v45
	global_store_dwordx2 v[56:57], v[44:45], off offset:-1536
	v_pk_mul_f32 v[42:43], v[42:43], v[50:51] op_sel_hi:[1,0]
	v_pk_mul_f32 v[44:45], v[40:41], v[50:51] op_sel_hi:[1,0]
	v_pk_fma_f32 v[40:41], v[6:7], v[42:43], v[14:15]
	v_pk_fma_f32 v[42:43], v[4:5], v[44:45], v[12:13]
	v_bfe_u32 v61, v41, 16, 1
	v_bfe_u32 v44, v42, 16, 1
	v_add3_u32 v44, v42, v44, s35
	v_bfe_u32 v45, v43, 16, 1
	v_lshrrev_b32_e32 v44, 16, v44
	v_add3_u32 v45, v43, v45, s35
	v_and_or_b32 v44, v45, s42, v44
	v_bfe_u32 v45, v40, 16, 1
	v_add3_u32 v45, v40, v45, s35
	v_lshrrev_b32_e32 v45, 16, v45
	v_add3_u32 v61, v41, v61, s35
	v_and_or_b32 v45, v61, s42, v45
	global_store_dwordx2 v[56:57], v[44:45], off offset:-1024
	v_pk_mul_f32 v[44:45], v[62:63], v[50:51] op_sel_hi:[1,0]
	v_pk_mul_f32 v[62:63], v[36:37], v[50:51] op_sel_hi:[1,0]
	v_pk_fma_f32 v[36:37], v[18:19], v[44:45], v[26:27]
	v_pk_fma_f32 v[44:45], v[16:17], v[62:63], v[24:25]
	v_bfe_u32 v63, v37, 16, 1
	v_bfe_u32 v61, v44, 16, 1
	v_add3_u32 v61, v44, v61, s35
	v_bfe_u32 v62, v45, 16, 1
	v_lshrrev_b32_e32 v61, 16, v61
	v_add3_u32 v62, v45, v62, s35
	v_and_or_b32 v62, v62, s42, v61
	v_bfe_u32 v61, v36, 16, 1
	v_add3_u32 v61, v36, v61, s35
	v_lshrrev_b32_e32 v61, 16, v61
	v_add3_u32 v63, v37, v63, s35
	v_and_or_b32 v63, v63, s42, v61
	global_store_dwordx2 v[56:57], v[62:63], off offset:-512
	v_pk_mul_f32 v[46:47], v[46:47], v[50:51] op_sel_hi:[1,0]
	v_pk_mul_f32 v[62:63], v[32:33], v[50:51] op_sel_hi:[1,0]
	v_pk_fma_f32 v[32:33], v[22:23], v[46:47], v[30:31]
	v_pk_fma_f32 v[46:47], v[20:21], v[62:63], v[28:29]
	v_bfe_u32 v71, v33, 16, 1
	v_bfe_u32 v50, v46, 16, 1
	v_add3_u32 v50, v46, v50, s35
	v_bfe_u32 v61, v47, 16, 1
	v_lshrrev_b32_e32 v50, 16, v50
	v_add3_u32 v61, v47, v61, s35
	v_and_or_b32 v72, v61, s42, v50
	v_bfe_u32 v50, v32, 16, 1
	v_add3_u32 v50, v32, v50, s35
	v_lshrrev_b32_e32 v61, 16, v50
	v_add_u32_e32 v50, 0, v48
	v_add3_u32 v71, v33, v71, s35
	v_and_or_b32 v73, v71, s42, v61
	global_store_dwordx2 v[56:57], v[72:73], off
	s_waitcnt lgkmcnt(0)
	v_pk_mul_f32 v[104:105], v[38:39], v[124:125]
	v_pk_mul_f32 v[106:107], v[38:39], v[140:141]
	v_pk_mul_f32 v[108:109], v[38:39], v[156:157]
	v_pk_mul_f32 v[110:111], v[38:39], v[172:173]
	v_pk_fma_f32 v[104:105], v[34:35], v[126:127], v[104:105]
	v_pk_fma_f32 v[106:107], v[34:35], v[142:143], v[106:107]
	v_pk_fma_f32 v[108:109], v[34:35], v[158:159], v[108:109]
	v_pk_fma_f32 v[110:111], v[34:35], v[174:175], v[110:111]
	ds_read_b128 v[124:127], v48 offset:16384
	ds_read_b128 v[140:143], v48 offset:20480
	ds_read_b128 v[156:159], v48 offset:24576
	ds_read_b128 v[172:175], v48 offset:28672
	v_pk_fma_f32 v[104:105], v[42:43], v[128:129], v[104:105]
	v_pk_fma_f32 v[106:107], v[42:43], v[144:145], v[106:107]
	v_pk_fma_f32 v[108:109], v[42:43], v[160:161], v[108:109]
	v_pk_fma_f32 v[110:111], v[42:43], v[176:177], v[110:111]
	v_pk_fma_f32 v[104:105], v[40:41], v[130:131], v[104:105]
	v_pk_fma_f32 v[106:107], v[40:41], v[146:147], v[106:107]
	v_pk_fma_f32 v[108:109], v[40:41], v[162:163], v[108:109]
	v_pk_fma_f32 v[110:111], v[40:41], v[178:179], v[110:111]
	ds_read_b128 v[128:131], v48 offset:17408
	ds_read_b128 v[144:147], v48 offset:21504
	ds_read_b128 v[160:163], v48 offset:25600
	ds_read_b128 v[176:179], v48 offset:29696
	v_pk_fma_f32 v[104:105], v[44:45], v[132:133], v[104:105]
	v_pk_fma_f32 v[106:107], v[44:45], v[148:149], v[106:107]
	v_pk_fma_f32 v[108:109], v[44:45], v[164:165], v[108:109]
	v_pk_fma_f32 v[110:111], v[44:45], v[180:181], v[110:111]
	v_pk_fma_f32 v[104:105], v[36:37], v[134:135], v[104:105]
	v_pk_fma_f32 v[106:107], v[36:37], v[150:151], v[106:107]
	v_pk_fma_f32 v[108:109], v[36:37], v[166:167], v[108:109]
	v_pk_fma_f32 v[110:111], v[36:37], v[182:183], v[110:111]
	ds_read_b128 v[132:135], v48 offset:18432
	ds_read_b128 v[148:151], v48 offset:22528
	ds_read_b128 v[164:167], v48 offset:26624
	ds_read_b128 v[180:183], v48 offset:30720
	v_pk_fma_f32 v[104:105], v[46:47], v[136:137], v[104:105]
	v_pk_fma_f32 v[106:107], v[46:47], v[152:153], v[106:107]
	v_pk_fma_f32 v[108:109], v[46:47], v[168:169], v[108:109]
	v_pk_fma_f32 v[110:111], v[46:47], v[184:185], v[110:111]
	v_pk_fma_f32 v[104:105], v[32:33], v[138:139], v[104:105]
	v_pk_fma_f32 v[106:107], v[32:33], v[154:155], v[106:107]
	v_pk_fma_f32 v[108:109], v[32:33], v[170:171], v[108:109]
	v_pk_fma_f32 v[110:111], v[32:33], v[186:187], v[110:111]
	ds_read_b128 v[136:139], v48 offset:19456
	ds_read_b128 v[152:155], v48 offset:23552
	ds_read_b128 v[168:171], v48 offset:27648
	ds_read_b128 v[184:187], v48 offset:31744
	v_add_f32_e32 v96, v104, v105
	v_add_f32_e32 v97, v106, v107
	v_add_f32_e32 v98, v108, v109
	v_add_f32_e32 v99, v110, v111
	s_waitcnt lgkmcnt(12)
	v_pk_mul_f32 v[104:105], v[38:39], v[124:125]
	v_pk_mul_f32 v[106:107], v[38:39], v[140:141]
	v_pk_mul_f32 v[108:109], v[38:39], v[156:157]
	v_pk_mul_f32 v[110:111], v[38:39], v[172:173]
	v_pk_fma_f32 v[104:105], v[34:35], v[126:127], v[104:105]
	v_pk_fma_f32 v[106:107], v[34:35], v[142:143], v[106:107]
	v_pk_fma_f32 v[108:109], v[34:35], v[158:159], v[108:109]
	v_pk_fma_f32 v[110:111], v[34:35], v[174:175], v[110:111]
	s_waitcnt lgkmcnt(8)
; #define LAS __attribute__((address_space(3)))
; template <int SRC, int EXTRA, bool OUT8 = false> ...
;     ...
;             for (int e = 0; e < 8; ++e) { float a = 0.f;
; #pragma unroll
;                 for (int j = 0; j < 4; ++j) { const f32x4 w = *(const LAS f32x4*)(w8s + e * 1024 + 256 * j + 4 * lane); a += (v[j].x * w.x + v[j].y * w.y) + (v[j].z * w.z + v[j].w * w.w); }
;                 d[e] = wave_sum(a); }
;             if (EXTRA == 1) {
;                 float x = d[0];
; #pragma unroll
;                 for (int e = 1; e < 8; ++e) x = (lane == e) ? d[e] : x;
	v_pk_fma_f32 v[104:105], v[42:43], v[128:129], v[104:105]
	v_pk_fma_f32 v[106:107], v[42:43], v[144:145], v[106:107]
	v_pk_fma_f32 v[108:109], v[42:43], v[160:161], v[108:109]
	v_pk_fma_f32 v[110:111], v[42:43], v[176:177], v[110:111]
	v_pk_fma_f32 v[104:105], v[40:41], v[130:131], v[104:105]
	v_pk_fma_f32 v[106:107], v[40:41], v[146:147], v[106:107]
	v_pk_fma_f32 v[108:109], v[40:41], v[162:163], v[108:109]
	v_pk_fma_f32 v[110:111], v[40:41], v[178:179], v[110:111]
	s_waitcnt lgkmcnt(4)
	v_pk_fma_f32 v[104:105], v[44:45], v[132:133], v[104:105]
	v_pk_fma_f32 v[106:107], v[44:45], v[148:149], v[106:107]
	v_pk_fma_f32 v[108:109], v[44:45], v[164:165], v[108:109]
	v_pk_fma_f32 v[110:111], v[44:45], v[180:181], v[110:111]
	v_pk_fma_f32 v[104:105], v[36:37], v[134:135], v[104:105]
	v_pk_fma_f32 v[106:107], v[36:37], v[150:151], v[106:107]
	v_pk_fma_f32 v[108:109], v[36:37], v[166:167], v[108:109]
	v_pk_fma_f32 v[110:111], v[36:37], v[182:183], v[110:111]
	s_waitcnt lgkmcnt(0)
	v_pk_fma_f32 v[104:105], v[46:47], v[136:137], v[104:105]
	v_pk_fma_f32 v[106:107], v[46:47], v[152:153], v[106:107]
	v_pk_fma_f32 v[108:109], v[46:47], v[168:169], v[108:109]
	v_pk_fma_f32 v[110:111], v[46:47], v[184:185], v[110:111]
	v_pk_fma_f32 v[104:105], v[32:33], v[138:139], v[104:105]
	v_pk_fma_f32 v[106:107], v[32:33], v[154:155], v[106:107]
	v_pk_fma_f32 v[108:109], v[32:33], v[170:171], v[108:109]
	v_pk_fma_f32 v[110:111], v[32:33], v[186:187], v[110:111]
	v_add_f32_e32 v100, v104, v105
	v_add_f32_e32 v101, v106, v107
	v_add_f32_e32 v102, v108, v109
	v_add_f32_e32 v103, v110, v111
	s_nop 0
	v_add_f32_dpp v104, v96, v96 quad_perm:[1,0,3,2] row_mask:0xf bank_mask:0xf
	v_add_f32_dpp v105, v97, v97 quad_perm:[1,0,3,2] row_mask:0xf bank_mask:0xf
	v_cndmask_b32_e64 v112, v104, v105, s[58:59]
	v_add_f32_dpp v106, v98, v98 quad_perm:[1,0,3,2] row_mask:0xf bank_mask:0xf
	v_add_f32_dpp v107, v99, v99 quad_perm:[1,0,3,2] row_mask:0xf bank_mask:0xf
	v_cndmask_b32_e64 v113, v106, v107, s[58:59]
	v_add_f32_dpp v108, v100, v100 quad_perm:[1,0,3,2] row_mask:0xf bank_mask:0xf
	v_add_f32_dpp v109, v101, v101 quad_perm:[1,0,3,2] row_mask:0xf bank_mask:0xf
	v_cndmask_b32_e64 v114, v108, v109, s[58:59]
	v_add_f32_dpp v110, v102, v102 quad_perm:[1,0,3,2] row_mask:0xf bank_mask:0xf
	v_add_f32_dpp v111, v103, v103 quad_perm:[1,0,3,2] row_mask:0xf bank_mask:0xf
	v_cndmask_b32_e64 v115, v110, v111, s[58:59]
	v_add_f32_dpp v104, v112, v112 quad_perm:[2,3,0,1] row_mask:0xf bank_mask:0xf
	v_add_f32_dpp v105, v113, v113 quad_perm:[2,3,0,1] row_mask:0xf bank_mask:0xf
	v_cndmask_b32_e64 v116, v104, v105, s[60:61]
	v_add_f32_dpp v106, v114, v114 quad_perm:[2,3,0,1] row_mask:0xf bank_mask:0xf
	v_add_f32_dpp v107, v115, v115 quad_perm:[2,3,0,1] row_mask:0xf bank_mask:0xf
	v_cndmask_b32_e64 v117, v106, v107, s[60:61]
	v_add_f32_dpp v104, v116, v116 row_shl:4 row_mask:0xf bank_mask:0x5
	v_add_f32_dpp v104, v116, v116 row_shr:4 row_mask:0xf bank_mask:0xa
	v_add_f32_dpp v105, v117, v117 row_shl:4 row_mask:0xf bank_mask:0x5
	v_add_f32_dpp v105, v117, v117 row_shr:4 row_mask:0xf bank_mask:0xa
	v_cndmask_b32_e64 v118, v104, v105, s[62:63]
	s_nop 1
	v_add_f32_dpp v119, v118, v118 row_ror:8 row_mask:0xf bank_mask:0xf
	v_mov_b32_e32 v104, v119
	v_mov_b32_e32 v120, v119
	s_nop 1
	v_permlane16_swap_b32_e32 v104, v120
	v_cndmask_b32_e64 v104, v120, v104, s[98:99]
	v_add_f32_e32 v119, v119, v104
	v_mov_b32_e32 v104, v119
	v_mov_b32_e32 v120, v119
	s_nop 1
	v_permlane32_swap_b32_e32 v104, v120
	v_cndmask_b32_e64 v104, v120, v104, s[100:101]
	v_add_f32_e32 v32, v119, v104
	s_and_saveexec_b64 s[28:29], s[12:13]
	s_cbranch_execz .LBB0_1056
; template <int SRC, int EXTRA, bool OUT8 = false> ...
;     ...
;             if (EXTRA == 1) {
;                 float x = d[0];
; #pragma unroll
;                 for (int e = 1; e < 8; ++e) x = (lane == e) ? d[e] : x;
;                 if (lane < 8) { x += bf8[lane]; const float ls = (x >= 0.f) ? -log1pf(__expf(-x)) : (x - log1pf(__expf(x))); logf[(size_t)lane * M + row] = ls; }
	v_add_f32_e32 v32, v32, v206
	v_mov_b32_e32 v121, v32
	v_and_b32_e32 v32, 0x7fffffff, v32
	s_mov_b64 s[52:53], exec
	v_mul_f32_e32 v32, 0xbfb8aa3b, v32
	v_exp_f32_e32 v46, v32
	s_nop 0
	v_add_f32_e32 v34, 1.0, v46
	v_frexp_mant_f32_e32 v36, v34
	v_cvt_f64_f32_e32 v[32:33], v34
	v_frexp_exp_i32_f64_e32 v32, v[32:33]
	v_cmp_gt_f32_e32 vcc, s43, v36
	v_add_f32_e32 v35, -1.0, v34
	v_sub_f32_e32 v37, v35, v34
	v_subbrev_co_u32_e32 v40, vcc, 0, v32, vcc
	v_sub_u32_e32 v32, 0, v40
	v_sub_f32_e32 v35, v46, v35
	v_add_f32_e32 v37, 1.0, v37
	v_ldexp_f32 v33, v34, v32
	v_add_f32_e32 v35, v35, v37
	v_add_f32_e32 v34, -1.0, v33
	v_add_f32_e32 v36, 1.0, v33
	v_ldexp_f32 v32, v35, v32
	v_add_f32_e32 v35, 1.0, v34
	v_add_f32_e32 v37, -1.0, v36
	v_sub_f32_e32 v35, v33, v35
	v_sub_f32_e32 v33, v33, v37
	v_add_f32_e32 v35, v32, v35
	v_add_f32_e32 v32, v32, v33
	v_add_f32_e32 v41, v36, v32
	v_rcp_f32_e32 v43, v41
	v_sub_f32_e32 v33, v41, v36
	v_sub_f32_e32 v42, v32, v33
	v_add_f32_e32 v33, v34, v35
	v_mul_f32_e32 v45, v33, v43
	v_sub_f32_e32 v32, v33, v34
	v_mul_f32_e32 v34, v41, v45
	v_fma_f32 v36, v45, v41, -v34
	v_fmac_f32_e32 v36, v45, v42
	v_sub_f32_e32 v44, v35, v32
	v_add_f32_e32 v32, v34, v36
	v_sub_f32_e32 v35, v33, v32
	v_pk_add_f32 v[38:39], v[32:33], v[34:35] neg_lo:[0,1] neg_hi:[0,1]
	v_mov_b32_e32 v37, v32
	v_pk_add_f32 v[32:33], v[38:39], v[36:37] neg_lo:[0,1] neg_hi:[0,1]
	v_cmp_neq_f32_e32 vcc, s55, v46
	v_add_f32_e32 v33, v44, v33
	v_add_f32_e32 v32, v32, v33
	v_add_f32_e32 v33, v35, v32
	v_mul_f32_e32 v44, v43, v33
	v_mul_f32_e32 v34, v41, v44
	v_fma_f32 v36, v44, v41, -v34
	v_fmac_f32_e32 v36, v44, v42
	v_sub_f32_e32 v35, v35, v33
	v_add_f32_e32 v41, v32, v35
	v_add_f32_e32 v32, v34, v36
	v_sub_f32_e32 v35, v33, v32
	v_pk_add_f32 v[38:39], v[32:33], v[34:35] neg_lo:[0,1] neg_hi:[0,1]
	v_mov_b32_e32 v37, v32
	v_pk_add_f32 v[32:33], v[38:39], v[36:37] neg_lo:[0,1] neg_hi:[0,1]
	s_nop 0
	v_add_f32_e32 v33, v41, v33
	v_add_f32_e32 v32, v32, v33
	v_add_f32_e32 v33, v45, v44
	v_add_f32_e32 v32, v35, v32
	v_sub_f32_e32 v34, v33, v45
	v_mul_f32_e32 v32, v43, v32
	v_sub_f32_e32 v34, v44, v34
	v_add_f32_e32 v34, v34, v32
	v_add_f32_e32 v36, v33, v34
	v_mul_f32_e32 v37, v36, v36
	v_fmamk_f32 v32, v37, 0x3e9b6dac, v67
	v_fmaak_f32 v61, v37, v32, 0x3f2aaada
	v_cvt_f32_i32_e32 v32, v40
	v_sub_f32_e32 v33, v36, v33
	v_sub_f32_e32 v33, v34, v33
	v_ldexp_f32 v38, v33, 1
	v_mul_f32_e32 v33, v36, v37
	v_ldexp_f32 v35, v36, 1
	v_pk_mul_f32 v[36:37], v[32:33], v[60:61]
	s_nop 0
	v_fma_f32 v34, v32, s54, -v36
	v_fmac_f32_e32 v34, 0xb102e308, v32
	v_pk_add_f32 v[32:33], v[36:37], v[34:35]
	s_nop 0
	v_sub_f32_e32 v35, v33, v35
	v_sub_f32_e32 v35, v37, v35
	v_add_f32_e32 v39, v38, v35
	v_mov_b32_e32 v38, v36
	v_pk_add_f32 v[36:37], v[32:33], v[36:37] neg_lo:[0,1] neg_hi:[0,1]
	v_pk_add_f32 v[40:41], v[32:33], v[38:39]
	v_mov_b32_e32 v35, v32
	v_mov_b32_e32 v37, v41
	v_pk_add_f32 v[42:43], v[34:35], v[36:37] neg_lo:[0,1] neg_hi:[0,1]
	v_pk_add_f32 v[34:35], v[34:35], v[36:37]
	v_mov_b32_e32 v38, v39
	v_pk_add_f32 v[36:37], v[34:35], v[32:33] op_sel:[1,0] op_sel_hi:[0,1] neg_lo:[0,1] neg_hi:[0,1]
	v_pk_add_f32 v[44:45], v[40:41], v[36:37] op_sel_hi:[1,0] neg_lo:[0,1] neg_hi:[0,1]
	v_mov_b32_e32 v40, v41
	v_mov_b32_e32 v41, v35
	v_pk_mov_b32 v[36:37], v[32:33], v[36:37] op_sel:[1,0]
	v_mov_b32_e32 v39, v32
	v_pk_add_f32 v[36:37], v[40:41], v[36:37] neg_lo:[0,1] neg_hi:[0,1]
	v_mov_b32_e32 v44, v42
	v_pk_add_f32 v[32:33], v[38:39], v[36:37] neg_lo:[0,1] neg_hi:[0,1]
	v_mov_b32_e32 v43, v35
	v_pk_add_f32 v[36:37], v[44:45], v[32:33]
	s_nop 0
	v_pk_add_f32 v[38:39], v[36:37], v[36:37] op_sel:[0,1] op_sel_hi:[1,0]
	s_nop 0
	v_pk_add_f32 v[34:35], v[34:35], v[38:39] op_sel:[1,0] op_sel_hi:[0,1]
	v_mov_b32_e32 v37, v34
	v_pk_add_f32 v[40:41], v[36:37], v[42:43] neg_lo:[0,1] neg_hi:[0,1]
	v_mov_b32_e32 v33, v38
	v_sub_f32_e32 v35, v36, v40
	v_pk_add_f32 v[32:33], v[32:33], v[40:41] neg_lo:[0,1] neg_hi:[0,1]
	v_sub_f32_e32 v35, v42, v35
	v_add_f32_e32 v32, v32, v35
	v_add_f32_e32 v32, v32, v33
	v_add_f32_e32 v32, v34, v32
	v_cndmask_b32_e32 v32, v68, v32, vcc
	v_cmp_ngt_f32_e32 vcc, -1.0, v46
	s_nop 1
	v_cndmask_b32_e32 v32, v69, v32, vcc
	v_cmp_neq_f32_e32 vcc, -1.0, v46
	s_nop 1
	v_cndmask_b32_e32 v32, v70, v32, vcc
	v_cmp_lt_f32_e64 vcc, |v46|, s56
	s_nop 1
	v_cndmask_b32_e32 v32, v32, v46, vcc
	v_xor_b32_e32 v33, 0x80000000, v32
	v_min_f32_e32 v121, 0, v121
	v_add_f32_e32 v33, v121, v33
	s_branch .LBB0_1055
